# c11 + tile stage rebalanced (waves 0-3: diagonal tile + inverse only; waves 4-7: four tiles), inverse one-hot init via scalar lane masks, one wait per column step
# baseline (speedup 1.0000x reference)
.Lgpf_skip:
	v_lshrrev_b32_e32 v207, 4, v3
	v_mul_u32_u24_e32 v116, 0x110, v206
	v_mul_u32_u24_e32 v115, 0x90, v206
	s_mov_b32 s27, 0x1a400
	v_lshlrev_b32_e32 v208, 3, v207
	v_lshlrev_b32_e32 v209, 3, v207
	v_lshl_add_u32 v116, v207, 4, v116
	v_lshl_add_u32 v117, v206, 2, s81
	v_lshl_add_u32 v114, v207, 4, s81
	v_add3_u32 v115, v115, v208, s27
	v_or_b32_e32 v118, s84, v206
	v_lshlrev_b32_e32 v119, 2, v207
	v_mul_u32_u24_e32 v136, 0x140, v207
	v_sub_u32_e32 v119, v206, v119
	v_lshl_add_u32 v136, v206, 2, v136
	v_add_u32_e32 v136, s97, v136
	s_cmp_lt_u32 s79, 4
	s_cbranch_scc1 .Lgt_lo
	s_cmp_lt_u32 s79, 6
	s_cbranch_scc1 .Lgt_45
	s_cmp_eq_u32 s79, 6
	s_cbranch_scc1 .Lgt_w6
	ds_read_b128 v[120:123], v116 offset:17408
	ds_read_b128 v[142:145], v116 offset:30464
	ds_read_b128 v[124:127], v116 offset:17472
	ds_read_b128 v[146:149], v116 offset:30528
	ds_read_b128 v[128:131], v116 offset:17536
	ds_read_b128 v[150:153], v116 offset:30592
	ds_read_b128 v[132:135], v116 offset:17600
	ds_read_b128 v[154:157], v116 offset:30656
	ds_read_b32 v112, v117 offset:192
	ds_read_b32 v113, v117 offset:2240
	ds_read_b128 v[160:163], v114 offset:0
	s_waitcnt lgkmcnt(9)
	v_mfma_f32_16x16x32_bf16 v[108:111], v[120:123], v[142:145], 0
	s_waitcnt lgkmcnt(7)
	v_mfma_f32_16x16x32_bf16 v[108:111], v[124:127], v[146:149], v[108:111]
	s_waitcnt lgkmcnt(5)
	v_mfma_f32_16x16x32_bf16 v[108:111], v[128:131], v[150:153], v[108:111]
	s_waitcnt lgkmcnt(3)
	v_mfma_f32_16x16x32_bf16 v[108:111], v[132:135], v[154:157], v[108:111]
	s_waitcnt lgkmcnt(0)
	v_sub_f32_e32 v164, v112, v160
	v_sub_f32_e32 v165, v112, v161
	v_sub_f32_e32 v166, v112, v162
	v_sub_f32_e32 v167, v112, v163
	v_mul_f32_e32 v164, 0x3fb8aa3b, v164
	v_mul_f32_e32 v165, 0x3fb8aa3b, v165
	v_mul_f32_e32 v166, 0x3fb8aa3b, v166
	v_mul_f32_e32 v167, 0x3fb8aa3b, v167
	v_exp_f32_e32 v164, v164
	v_exp_f32_e32 v165, v165
	v_exp_f32_e32 v166, v166
	v_exp_f32_e32 v167, v167
	v_mul_f32_e32 v108, v108, v113
	v_mul_f32_e32 v109, v109, v113
	v_mul_f32_e32 v110, v110, v113
	v_mul_f32_e32 v111, v111, v113
	v_mul_f32_e32 v108, v108, v164
	v_mul_f32_e32 v109, v109, v165
	v_mul_f32_e32 v110, v110, v166
	v_mul_f32_e32 v111, v111, v167
	v_cvt_pk_bf16_f32 v168, -v108, -v109
	v_cvt_pk_bf16_f32 v169, -v110, -v111
	ds_write_b64 v115, v[168:169] offset:23808
	ds_read_b128 v[120:123], v116 offset:21760
	ds_read_b128 v[142:145], v116 offset:13056
	ds_read_b128 v[124:127], v116 offset:21824
	ds_read_b128 v[146:149], v116 offset:13120
	ds_read_b128 v[128:131], v116 offset:21888
	ds_read_b128 v[150:153], v116 offset:13184
	ds_read_b128 v[132:135], v116 offset:21952
	ds_read_b128 v[154:157], v116 offset:13248
	ds_read_b32 v112, v117 offset:192
	ds_read_b128 v[160:163], v114 offset:64
	s_waitcnt lgkmcnt(8)
	v_mfma_f32_16x16x32_bf16 v[108:111], v[120:123], v[142:145], 0
	s_waitcnt lgkmcnt(6)
	v_mfma_f32_16x16x32_bf16 v[108:111], v[124:127], v[146:149], v[108:111]
	s_waitcnt lgkmcnt(4)
	v_mfma_f32_16x16x32_bf16 v[108:111], v[128:131], v[150:153], v[108:111]
	s_waitcnt lgkmcnt(2)
	v_mfma_f32_16x16x32_bf16 v[108:111], v[132:135], v[154:157], v[108:111]
	s_waitcnt lgkmcnt(0)
	v_sub_f32_e32 v164, v112, v160
	v_sub_f32_e32 v165, v112, v161
	v_sub_f32_e32 v166, v112, v162
	v_sub_f32_e32 v167, v112, v163
	v_mul_f32_e32 v164, 0x3fb8aa3b, v164
	v_mul_f32_e32 v165, 0x3fb8aa3b, v165
	v_mul_f32_e32 v166, 0x3fb8aa3b, v166
	v_mul_f32_e32 v167, 0x3fb8aa3b, v167
	v_exp_f32_e32 v164, v164
	v_exp_f32_e32 v165, v165
	v_exp_f32_e32 v166, v166
	v_exp_f32_e32 v167, v167
	v_mul_f32_e32 v108, v108, v164
	v_mul_f32_e32 v109, v109, v165
	v_mul_f32_e32 v110, v110, v166
	v_mul_f32_e32 v111, v111, v167
	v_cvt_pk_bf16_f32 v168, v108, v109
	v_cvt_pk_bf16_f32 v169, v110, v111
	ds_write_b64 v115, v[168:169] offset:6944
	ds_read_b128 v[120:123], v116 offset:26112
	ds_read_b128 v[142:145], v116 offset:13056
	ds_read_b128 v[124:127], v116 offset:26176
	ds_read_b128 v[146:149], v116 offset:13120
	ds_read_b128 v[128:131], v116 offset:26240
	ds_read_b128 v[150:153], v116 offset:13184
	ds_read_b128 v[132:135], v116 offset:26304
	ds_read_b128 v[154:157], v116 offset:13248
	ds_read_b32 v112, v117 offset:192
	ds_read_b128 v[160:163], v114 offset:128
	s_waitcnt lgkmcnt(8)
	v_mfma_f32_16x16x32_bf16 v[108:111], v[120:123], v[142:145], 0
	s_waitcnt lgkmcnt(6)
	v_mfma_f32_16x16x32_bf16 v[108:111], v[124:127], v[146:149], v[108:111]
	s_waitcnt lgkmcnt(4)
	v_mfma_f32_16x16x32_bf16 v[108:111], v[128:131], v[150:153], v[108:111]
	s_waitcnt lgkmcnt(2)
	v_mfma_f32_16x16x32_bf16 v[108:111], v[132:135], v[154:157], v[108:111]
	s_waitcnt lgkmcnt(0)
	v_sub_f32_e32 v164, v112, v160
	v_sub_f32_e32 v165, v112, v161
	v_sub_f32_e32 v166, v112, v162
	v_sub_f32_e32 v167, v112, v163
	v_mul_f32_e32 v164, 0x3fb8aa3b, v164
	v_mul_f32_e32 v165, 0x3fb8aa3b, v165
	v_mul_f32_e32 v166, 0x3fb8aa3b, v166
	v_mul_f32_e32 v167, 0x3fb8aa3b, v167
	v_exp_f32_e32 v164, v164
	v_exp_f32_e32 v165, v165
	v_exp_f32_e32 v166, v166
	v_exp_f32_e32 v167, v167
	v_mul_f32_e32 v108, v108, v164
	v_mul_f32_e32 v109, v109, v165
	v_mul_f32_e32 v110, v110, v166
	v_mul_f32_e32 v111, v111, v167
	v_cvt_pk_bf16_f32 v168, v108, v109
	v_cvt_pk_bf16_f32 v169, v110, v111
	ds_write_b64 v115, v[168:169] offset:6976
	ds_read_b128 v[120:123], v116 offset:30464
	ds_read_b128 v[142:145], v116 offset:13056
	ds_read_b128 v[124:127], v116 offset:30528
	ds_read_b128 v[146:149], v116 offset:13120
	ds_read_b128 v[128:131], v116 offset:30592
	ds_read_b128 v[150:153], v116 offset:13184
	ds_read_b128 v[132:135], v116 offset:30656
	ds_read_b128 v[154:157], v116 offset:13248
	ds_read_b32 v112, v117 offset:192
	ds_read_b128 v[160:163], v114 offset:192
	v_cmp_le_i32_e64 s[10:11], 0, v119
	v_cmp_le_i32_e64 s[12:13], 1, v119
	v_cmp_le_i32_e64 s[48:49], 2, v119
	v_cmp_le_i32_e64 s[50:51], 3, v119
	s_waitcnt lgkmcnt(8)
	v_mfma_f32_16x16x32_bf16 v[108:111], v[120:123], v[142:145], 0
	s_waitcnt lgkmcnt(6)
	v_mfma_f32_16x16x32_bf16 v[108:111], v[124:127], v[146:149], v[108:111]
	s_waitcnt lgkmcnt(4)
	v_mfma_f32_16x16x32_bf16 v[108:111], v[128:131], v[150:153], v[108:111]
	s_waitcnt lgkmcnt(2)
	v_mfma_f32_16x16x32_bf16 v[108:111], v[132:135], v[154:157], v[108:111]
	s_waitcnt lgkmcnt(0)
	v_sub_f32_e32 v164, v112, v160
	v_sub_f32_e32 v165, v112, v161
	v_sub_f32_e32 v166, v112, v162
	v_sub_f32_e32 v167, v112, v163
	v_mul_f32_e32 v164, 0x3fb8aa3b, v164
	v_mul_f32_e32 v165, 0x3fb8aa3b, v165
	v_mul_f32_e32 v166, 0x3fb8aa3b, v166
	v_mul_f32_e32 v167, 0x3fb8aa3b, v167
	v_exp_f32_e32 v164, v164
	v_exp_f32_e32 v165, v165
	v_exp_f32_e32 v166, v166
	v_exp_f32_e32 v167, v167
	v_mul_f32_e32 v108, v108, v164
	v_mul_f32_e32 v109, v109, v165
	v_mul_f32_e32 v110, v110, v166
	v_mul_f32_e32 v111, v111, v167
	v_cndmask_b32_e64 v108, 0, v108, s[10:11]
	v_cndmask_b32_e64 v109, 0, v109, s[12:13]
	v_cndmask_b32_e64 v110, 0, v110, s[48:49]
	v_cndmask_b32_e64 v111, 0, v111, s[50:51]
	v_cvt_pk_bf16_f32 v168, v108, v109
	v_cvt_pk_bf16_f32 v169, v110, v111
	ds_write_b64 v115, v[168:169] offset:7008
	s_branch .Lgt_end
.Lgt_w6:
	ds_read_b128 v[120:123], v116 offset:21760
	ds_read_b128 v[142:145], v116 offset:26112
	ds_read_b128 v[124:127], v116 offset:21824
	ds_read_b128 v[146:149], v116 offset:26176
	ds_read_b128 v[128:131], v116 offset:21888
	ds_read_b128 v[150:153], v116 offset:26240
	ds_read_b128 v[132:135], v116 offset:21952
	ds_read_b128 v[154:157], v116 offset:26304
	ds_read_b32 v112, v117 offset:128
	ds_read_b32 v113, v117 offset:2176
	ds_read_b128 v[160:163], v114 offset:64
	s_waitcnt lgkmcnt(9)
	v_mfma_f32_16x16x32_bf16 v[108:111], v[120:123], v[142:145], 0
	s_waitcnt lgkmcnt(7)
	v_mfma_f32_16x16x32_bf16 v[108:111], v[124:127], v[146:149], v[108:111]
	s_waitcnt lgkmcnt(5)
	v_mfma_f32_16x16x32_bf16 v[108:111], v[128:131], v[150:153], v[108:111]
	s_waitcnt lgkmcnt(3)
	v_mfma_f32_16x16x32_bf16 v[108:111], v[132:135], v[154:157], v[108:111]
	s_waitcnt lgkmcnt(0)
	v_sub_f32_e32 v164, v112, v160
	v_sub_f32_e32 v165, v112, v161
	v_sub_f32_e32 v166, v112, v162
	v_sub_f32_e32 v167, v112, v163
	v_mul_f32_e32 v164, 0x3fb8aa3b, v164
	v_mul_f32_e32 v165, 0x3fb8aa3b, v165
	v_mul_f32_e32 v166, 0x3fb8aa3b, v166
	v_mul_f32_e32 v167, 0x3fb8aa3b, v167
	v_exp_f32_e32 v164, v164
	v_exp_f32_e32 v165, v165
	v_exp_f32_e32 v166, v166
	v_exp_f32_e32 v167, v167
	v_mul_f32_e32 v108, v108, v113
	v_mul_f32_e32 v109, v109, v113
	v_mul_f32_e32 v110, v110, v113
	v_mul_f32_e32 v111, v111, v113
	v_mul_f32_e32 v108, v108, v164
	v_mul_f32_e32 v109, v109, v165
	v_mul_f32_e32 v110, v110, v166
	v_mul_f32_e32 v111, v111, v167
	v_cvt_pk_bf16_f32 v168, -v108, -v109
	v_cvt_pk_bf16_f32 v169, -v110, -v111
	ds_write_b64 v115, v[168:169] offset:21536
	ds_read_b128 v[120:123], v116 offset:21760
	ds_read_b128 v[142:145], v116 offset:8704
	ds_read_b128 v[124:127], v116 offset:21824
	ds_read_b128 v[146:149], v116 offset:8768
	ds_read_b128 v[128:131], v116 offset:21888
	ds_read_b128 v[150:153], v116 offset:8832
	ds_read_b128 v[132:135], v116 offset:21952
	ds_read_b128 v[154:157], v116 offset:8896
	ds_read_b32 v112, v117 offset:128
	ds_read_b128 v[160:163], v114 offset:64
	s_waitcnt lgkmcnt(8)
	v_mfma_f32_16x16x32_bf16 v[108:111], v[120:123], v[142:145], 0
	s_waitcnt lgkmcnt(6)
	v_mfma_f32_16x16x32_bf16 v[108:111], v[124:127], v[146:149], v[108:111]
	s_waitcnt lgkmcnt(4)
	v_mfma_f32_16x16x32_bf16 v[108:111], v[128:131], v[150:153], v[108:111]
	s_waitcnt lgkmcnt(2)
	v_mfma_f32_16x16x32_bf16 v[108:111], v[132:135], v[154:157], v[108:111]
	s_waitcnt lgkmcnt(0)
	v_sub_f32_e32 v164, v112, v160
	v_sub_f32_e32 v165, v112, v161
	v_sub_f32_e32 v166, v112, v162
	v_sub_f32_e32 v167, v112, v163
	v_mul_f32_e32 v164, 0x3fb8aa3b, v164
	v_mul_f32_e32 v165, 0x3fb8aa3b, v165
	v_mul_f32_e32 v166, 0x3fb8aa3b, v166
	v_mul_f32_e32 v167, 0x3fb8aa3b, v167
	v_exp_f32_e32 v164, v164
	v_exp_f32_e32 v165, v165
	v_exp_f32_e32 v166, v166
	v_exp_f32_e32 v167, v167
	v_mul_f32_e32 v108, v108, v164
	v_mul_f32_e32 v109, v109, v165
	v_mul_f32_e32 v110, v110, v166
	v_mul_f32_e32 v111, v111, v167
	v_cvt_pk_bf16_f32 v168, v108, v109
	v_cvt_pk_bf16_f32 v169, v110, v111
	ds_write_b64 v115, v[168:169] offset:4640
	ds_read_b128 v[120:123], v116 offset:26112
	ds_read_b128 v[142:145], v116 offset:8704
	ds_read_b128 v[124:127], v116 offset:26176
	ds_read_b128 v[146:149], v116 offset:8768
	ds_read_b128 v[128:131], v116 offset:26240
	ds_read_b128 v[150:153], v116 offset:8832
	ds_read_b128 v[132:135], v116 offset:26304
	ds_read_b128 v[154:157], v116 offset:8896
	ds_read_b32 v112, v117 offset:128
	ds_read_b128 v[160:163], v114 offset:128
	v_cmp_le_i32_e64 s[10:11], 0, v119
	v_cmp_le_i32_e64 s[12:13], 1, v119
	v_cmp_le_i32_e64 s[48:49], 2, v119
	v_cmp_le_i32_e64 s[50:51], 3, v119
	s_waitcnt lgkmcnt(8)
	v_mfma_f32_16x16x32_bf16 v[108:111], v[120:123], v[142:145], 0
	s_waitcnt lgkmcnt(6)
	v_mfma_f32_16x16x32_bf16 v[108:111], v[124:127], v[146:149], v[108:111]
	s_waitcnt lgkmcnt(4)
	v_mfma_f32_16x16x32_bf16 v[108:111], v[128:131], v[150:153], v[108:111]
	s_waitcnt lgkmcnt(2)
	v_mfma_f32_16x16x32_bf16 v[108:111], v[132:135], v[154:157], v[108:111]
	s_waitcnt lgkmcnt(0)
	v_sub_f32_e32 v164, v112, v160
	v_sub_f32_e32 v165, v112, v161
	v_sub_f32_e32 v166, v112, v162
	v_sub_f32_e32 v167, v112, v163
	v_mul_f32_e32 v164, 0x3fb8aa3b, v164
	v_mul_f32_e32 v165, 0x3fb8aa3b, v165
	v_mul_f32_e32 v166, 0x3fb8aa3b, v166
	v_mul_f32_e32 v167, 0x3fb8aa3b, v167
	v_exp_f32_e32 v164, v164
	v_exp_f32_e32 v165, v165
	v_exp_f32_e32 v166, v166
	v_exp_f32_e32 v167, v167
	v_mul_f32_e32 v108, v108, v164
	v_mul_f32_e32 v109, v109, v165
	v_mul_f32_e32 v110, v110, v166
	v_mul_f32_e32 v111, v111, v167
	v_cndmask_b32_e64 v108, 0, v108, s[10:11]
	v_cndmask_b32_e64 v109, 0, v109, s[12:13]
	v_cndmask_b32_e64 v110, 0, v110, s[48:49]
	v_cndmask_b32_e64 v111, 0, v111, s[50:51]
	v_cvt_pk_bf16_f32 v168, v108, v109
	v_cvt_pk_bf16_f32 v169, v110, v111
	ds_write_b64 v115, v[168:169] offset:4672
	ds_read_b128 v[120:123], v116 offset:17408
	ds_read_b128 v[142:145], v116 offset:13056
	ds_read_b128 v[124:127], v116 offset:17472
	ds_read_b128 v[146:149], v116 offset:13120
	ds_read_b128 v[128:131], v116 offset:17536
	ds_read_b128 v[150:153], v116 offset:13184
	ds_read_b128 v[132:135], v116 offset:17600
	ds_read_b128 v[154:157], v116 offset:13248
	ds_read_b32 v112, v117 offset:192
	ds_read_b128 v[160:163], v114 offset:0
	s_waitcnt lgkmcnt(8)
	v_mfma_f32_16x16x32_bf16 v[108:111], v[120:123], v[142:145], 0
	s_waitcnt lgkmcnt(6)
	v_mfma_f32_16x16x32_bf16 v[108:111], v[124:127], v[146:149], v[108:111]
	s_waitcnt lgkmcnt(4)
	v_mfma_f32_16x16x32_bf16 v[108:111], v[128:131], v[150:153], v[108:111]
	s_waitcnt lgkmcnt(2)
	v_mfma_f32_16x16x32_bf16 v[108:111], v[132:135], v[154:157], v[108:111]
	s_waitcnt lgkmcnt(0)
	v_sub_f32_e32 v164, v112, v160
	v_sub_f32_e32 v165, v112, v161
	v_sub_f32_e32 v166, v112, v162
	v_sub_f32_e32 v167, v112, v163
	v_mul_f32_e32 v164, 0x3fb8aa3b, v164
	v_mul_f32_e32 v165, 0x3fb8aa3b, v165
	v_mul_f32_e32 v166, 0x3fb8aa3b, v166
	v_mul_f32_e32 v167, 0x3fb8aa3b, v167
	v_exp_f32_e32 v164, v164
	v_exp_f32_e32 v165, v165
	v_exp_f32_e32 v166, v166
	v_exp_f32_e32 v167, v167
	v_mul_f32_e32 v108, v108, v164
	v_mul_f32_e32 v109, v109, v165
	v_mul_f32_e32 v110, v110, v166
	v_mul_f32_e32 v111, v111, v167
	v_cvt_pk_bf16_f32 v168, v108, v109
	v_cvt_pk_bf16_f32 v169, v110, v111
	ds_write_b64 v115, v[168:169] offset:6912
	s_branch .Lgt_end
.Lgt_45:
	s_cmp_eq_u32 s79, 4
	s_cbranch_scc1 .Lgt_w4
	ds_read_b128 v[120:123], v116 offset:17408
	ds_read_b128 v[142:145], v116 offset:26112
	ds_read_b128 v[124:127], v116 offset:17472
	ds_read_b128 v[146:149], v116 offset:26176
	ds_read_b128 v[128:131], v116 offset:17536
	ds_read_b128 v[150:153], v116 offset:26240
	ds_read_b128 v[132:135], v116 offset:17600
	ds_read_b128 v[154:157], v116 offset:26304
	ds_read_b32 v112, v117 offset:128
	ds_read_b32 v113, v117 offset:2176
	ds_read_b128 v[160:163], v114 offset:0
	s_waitcnt lgkmcnt(9)
	v_mfma_f32_16x16x32_bf16 v[108:111], v[120:123], v[142:145], 0
	s_waitcnt lgkmcnt(7)
	v_mfma_f32_16x16x32_bf16 v[108:111], v[124:127], v[146:149], v[108:111]
	s_waitcnt lgkmcnt(5)
	v_mfma_f32_16x16x32_bf16 v[108:111], v[128:131], v[150:153], v[108:111]
	s_waitcnt lgkmcnt(3)
	v_mfma_f32_16x16x32_bf16 v[108:111], v[132:135], v[154:157], v[108:111]
	s_waitcnt lgkmcnt(0)
	v_sub_f32_e32 v164, v112, v160
	v_sub_f32_e32 v165, v112, v161
	v_sub_f32_e32 v166, v112, v162
	v_sub_f32_e32 v167, v112, v163
	v_mul_f32_e32 v164, 0x3fb8aa3b, v164
	v_mul_f32_e32 v165, 0x3fb8aa3b, v165
	v_mul_f32_e32 v166, 0x3fb8aa3b, v166
	v_mul_f32_e32 v167, 0x3fb8aa3b, v167
	v_exp_f32_e32 v164, v164
	v_exp_f32_e32 v165, v165
	v_exp_f32_e32 v166, v166
	v_exp_f32_e32 v167, v167
	v_mul_f32_e32 v108, v108, v113
	v_mul_f32_e32 v109, v109, v113
	v_mul_f32_e32 v110, v110, v113
	v_mul_f32_e32 v111, v111, v113
	v_mul_f32_e32 v108, v108, v164
	v_mul_f32_e32 v109, v109, v165
	v_mul_f32_e32 v110, v110, v166
	v_mul_f32_e32 v111, v111, v167
	v_cvt_pk_bf16_f32 v168, -v108, -v109
	v_cvt_pk_bf16_f32 v169, -v110, -v111
	ds_write_b64 v115, v[168:169] offset:21504
	ds_read_b128 v[120:123], v116 offset:17408
	ds_read_b128 v[142:145], v116 offset:4352
	ds_read_b128 v[124:127], v116 offset:17472
	ds_read_b128 v[146:149], v116 offset:4416
	ds_read_b128 v[128:131], v116 offset:17536
	ds_read_b128 v[150:153], v116 offset:4480
	ds_read_b128 v[132:135], v116 offset:17600
	ds_read_b128 v[154:157], v116 offset:4544
	ds_read_b32 v112, v117 offset:64
	ds_read_b128 v[160:163], v114 offset:0
	s_waitcnt lgkmcnt(8)
	v_mfma_f32_16x16x32_bf16 v[108:111], v[120:123], v[142:145], 0
	s_waitcnt lgkmcnt(6)
	v_mfma_f32_16x16x32_bf16 v[108:111], v[124:127], v[146:149], v[108:111]
	s_waitcnt lgkmcnt(4)
	v_mfma_f32_16x16x32_bf16 v[108:111], v[128:131], v[150:153], v[108:111]
	s_waitcnt lgkmcnt(2)
	v_mfma_f32_16x16x32_bf16 v[108:111], v[132:135], v[154:157], v[108:111]
	s_waitcnt lgkmcnt(0)
	v_sub_f32_e32 v164, v112, v160
	v_sub_f32_e32 v165, v112, v161
	v_sub_f32_e32 v166, v112, v162
	v_sub_f32_e32 v167, v112, v163
	v_mul_f32_e32 v164, 0x3fb8aa3b, v164
	v_mul_f32_e32 v165, 0x3fb8aa3b, v165
	v_mul_f32_e32 v166, 0x3fb8aa3b, v166
	v_mul_f32_e32 v167, 0x3fb8aa3b, v167
	v_exp_f32_e32 v164, v164
	v_exp_f32_e32 v165, v165
	v_exp_f32_e32 v166, v166
	v_exp_f32_e32 v167, v167
	v_mul_f32_e32 v108, v108, v164
	v_mul_f32_e32 v109, v109, v165
	v_mul_f32_e32 v110, v110, v166
	v_mul_f32_e32 v111, v111, v167
	v_cvt_pk_bf16_f32 v168, v108, v109
	v_cvt_pk_bf16_f32 v169, v110, v111
	ds_write_b64 v115, v[168:169] offset:2304
	ds_read_b128 v[120:123], v116 offset:21760
	ds_read_b128 v[142:145], v116 offset:4352
	ds_read_b128 v[124:127], v116 offset:21824
	ds_read_b128 v[146:149], v116 offset:4416
	ds_read_b128 v[128:131], v116 offset:21888
	ds_read_b128 v[150:153], v116 offset:4480
	ds_read_b128 v[132:135], v116 offset:21952
	ds_read_b128 v[154:157], v116 offset:4544
	ds_read_b32 v112, v117 offset:64
	ds_read_b128 v[160:163], v114 offset:64
	v_cmp_le_i32_e64 s[10:11], 0, v119
	v_cmp_le_i32_e64 s[12:13], 1, v119
	v_cmp_le_i32_e64 s[48:49], 2, v119
	v_cmp_le_i32_e64 s[50:51], 3, v119
	s_waitcnt lgkmcnt(8)
	v_mfma_f32_16x16x32_bf16 v[108:111], v[120:123], v[142:145], 0
	s_waitcnt lgkmcnt(6)
	v_mfma_f32_16x16x32_bf16 v[108:111], v[124:127], v[146:149], v[108:111]
	s_waitcnt lgkmcnt(4)
	v_mfma_f32_16x16x32_bf16 v[108:111], v[128:131], v[150:153], v[108:111]
	s_waitcnt lgkmcnt(2)
	v_mfma_f32_16x16x32_bf16 v[108:111], v[132:135], v[154:157], v[108:111]
	s_waitcnt lgkmcnt(0)
	v_sub_f32_e32 v164, v112, v160
	v_sub_f32_e32 v165, v112, v161
	v_sub_f32_e32 v166, v112, v162
	v_sub_f32_e32 v167, v112, v163
	v_mul_f32_e32 v164, 0x3fb8aa3b, v164
	v_mul_f32_e32 v165, 0x3fb8aa3b, v165
	v_mul_f32_e32 v166, 0x3fb8aa3b, v166
	v_mul_f32_e32 v167, 0x3fb8aa3b, v167
	v_exp_f32_e32 v164, v164
	v_exp_f32_e32 v165, v165
	v_exp_f32_e32 v166, v166
	v_exp_f32_e32 v167, v167
	v_mul_f32_e32 v108, v108, v164
	v_mul_f32_e32 v109, v109, v165
	v_mul_f32_e32 v110, v110, v166
	v_mul_f32_e32 v111, v111, v167
	v_cndmask_b32_e64 v108, 0, v108, s[10:11]
	v_cndmask_b32_e64 v109, 0, v109, s[12:13]
	v_cndmask_b32_e64 v110, 0, v110, s[48:49]
	v_cndmask_b32_e64 v111, 0, v111, s[50:51]
	v_cvt_pk_bf16_f32 v168, v108, v109
	v_cvt_pk_bf16_f32 v169, v110, v111
	ds_write_b64 v115, v[168:169] offset:2336
	ds_read_b128 v[120:123], v116 offset:17408
	ds_read_b128 v[142:145], v116 offset:8704
	ds_read_b128 v[124:127], v116 offset:17472
	ds_read_b128 v[146:149], v116 offset:8768
	ds_read_b128 v[128:131], v116 offset:17536
	ds_read_b128 v[150:153], v116 offset:8832
	ds_read_b128 v[132:135], v116 offset:17600
	ds_read_b128 v[154:157], v116 offset:8896
	ds_read_b32 v112, v117 offset:128
	ds_read_b128 v[160:163], v114 offset:0
	s_waitcnt lgkmcnt(8)
	v_mfma_f32_16x16x32_bf16 v[108:111], v[120:123], v[142:145], 0
	s_waitcnt lgkmcnt(6)
	v_mfma_f32_16x16x32_bf16 v[108:111], v[124:127], v[146:149], v[108:111]
	s_waitcnt lgkmcnt(4)
	v_mfma_f32_16x16x32_bf16 v[108:111], v[128:131], v[150:153], v[108:111]
	s_waitcnt lgkmcnt(2)
	v_mfma_f32_16x16x32_bf16 v[108:111], v[132:135], v[154:157], v[108:111]
	s_waitcnt lgkmcnt(0)
	v_sub_f32_e32 v164, v112, v160
	v_sub_f32_e32 v165, v112, v161
	v_sub_f32_e32 v166, v112, v162
	v_sub_f32_e32 v167, v112, v163
	v_mul_f32_e32 v164, 0x3fb8aa3b, v164
	v_mul_f32_e32 v165, 0x3fb8aa3b, v165
	v_mul_f32_e32 v166, 0x3fb8aa3b, v166
	v_mul_f32_e32 v167, 0x3fb8aa3b, v167
	v_exp_f32_e32 v164, v164
	v_exp_f32_e32 v165, v165
	v_exp_f32_e32 v166, v166
	v_exp_f32_e32 v167, v167
	v_mul_f32_e32 v108, v108, v164
	v_mul_f32_e32 v109, v109, v165
	v_mul_f32_e32 v110, v110, v166
	v_mul_f32_e32 v111, v111, v167
	v_cvt_pk_bf16_f32 v168, v108, v109
	v_cvt_pk_bf16_f32 v169, v110, v111
	ds_write_b64 v115, v[168:169] offset:4608
	s_branch .Lgt_end
.Lgt_w4:
	ds_read_b128 v[120:123], v116 offset:17408
	ds_read_b128 v[142:145], v116 offset:21760
	ds_read_b128 v[124:127], v116 offset:17472
	ds_read_b128 v[146:149], v116 offset:21824
	ds_read_b128 v[128:131], v116 offset:17536
	ds_read_b128 v[150:153], v116 offset:21888
	ds_read_b128 v[132:135], v116 offset:17600
	ds_read_b128 v[154:157], v116 offset:21952
	ds_read_b32 v112, v117 offset:64
	ds_read_b32 v113, v117 offset:2112
	ds_read_b128 v[160:163], v114 offset:0
	s_waitcnt lgkmcnt(9)
	v_mfma_f32_16x16x32_bf16 v[108:111], v[120:123], v[142:145], 0
	s_waitcnt lgkmcnt(7)
	v_mfma_f32_16x16x32_bf16 v[108:111], v[124:127], v[146:149], v[108:111]
	s_waitcnt lgkmcnt(5)
	v_mfma_f32_16x16x32_bf16 v[108:111], v[128:131], v[150:153], v[108:111]
	s_waitcnt lgkmcnt(3)
	v_mfma_f32_16x16x32_bf16 v[108:111], v[132:135], v[154:157], v[108:111]
	s_waitcnt lgkmcnt(0)
	v_sub_f32_e32 v164, v112, v160
	v_sub_f32_e32 v165, v112, v161
	v_sub_f32_e32 v166, v112, v162
	v_sub_f32_e32 v167, v112, v163
	v_mul_f32_e32 v164, 0x3fb8aa3b, v164
	v_mul_f32_e32 v165, 0x3fb8aa3b, v165
	v_mul_f32_e32 v166, 0x3fb8aa3b, v166
	v_mul_f32_e32 v167, 0x3fb8aa3b, v167
	v_exp_f32_e32 v164, v164
	v_exp_f32_e32 v165, v165
	v_exp_f32_e32 v166, v166
	v_exp_f32_e32 v167, v167
	v_mul_f32_e32 v108, v108, v113
	v_mul_f32_e32 v109, v109, v113
	v_mul_f32_e32 v110, v110, v113
	v_mul_f32_e32 v111, v111, v113
	v_mul_f32_e32 v108, v108, v164
	v_mul_f32_e32 v109, v109, v165
	v_mul_f32_e32 v110, v110, v166
	v_mul_f32_e32 v111, v111, v167
	v_cvt_pk_bf16_f32 v168, -v108, -v109
	v_cvt_pk_bf16_f32 v169, -v110, -v111
	ds_write_b64 v115, v[168:169] offset:19200
	ds_read_b128 v[120:123], v116 offset:21760
	ds_read_b128 v[142:145], v116 offset:30464
	ds_read_b128 v[124:127], v116 offset:21824
	ds_read_b128 v[146:149], v116 offset:30528
	ds_read_b128 v[128:131], v116 offset:21888
	ds_read_b128 v[150:153], v116 offset:30592
	ds_read_b128 v[132:135], v116 offset:21952
	ds_read_b128 v[154:157], v116 offset:30656
	ds_read_b32 v112, v117 offset:192
	ds_read_b32 v113, v117 offset:2240
	ds_read_b128 v[160:163], v114 offset:64
	s_waitcnt lgkmcnt(9)
	v_mfma_f32_16x16x32_bf16 v[108:111], v[120:123], v[142:145], 0
	s_waitcnt lgkmcnt(7)
	v_mfma_f32_16x16x32_bf16 v[108:111], v[124:127], v[146:149], v[108:111]
	s_waitcnt lgkmcnt(5)
	v_mfma_f32_16x16x32_bf16 v[108:111], v[128:131], v[150:153], v[108:111]
	s_waitcnt lgkmcnt(3)
	v_mfma_f32_16x16x32_bf16 v[108:111], v[132:135], v[154:157], v[108:111]
	s_waitcnt lgkmcnt(0)
	v_sub_f32_e32 v164, v112, v160
	v_sub_f32_e32 v165, v112, v161
	v_sub_f32_e32 v166, v112, v162
	v_sub_f32_e32 v167, v112, v163
	v_mul_f32_e32 v164, 0x3fb8aa3b, v164
	v_mul_f32_e32 v165, 0x3fb8aa3b, v165
	v_mul_f32_e32 v166, 0x3fb8aa3b, v166
	v_mul_f32_e32 v167, 0x3fb8aa3b, v167
	v_exp_f32_e32 v164, v164
	v_exp_f32_e32 v165, v165
	v_exp_f32_e32 v166, v166
	v_exp_f32_e32 v167, v167
	v_mul_f32_e32 v108, v108, v113
	v_mul_f32_e32 v109, v109, v113
	v_mul_f32_e32 v110, v110, v113
	v_mul_f32_e32 v111, v111, v113
	v_mul_f32_e32 v108, v108, v164
	v_mul_f32_e32 v109, v109, v165
	v_mul_f32_e32 v110, v110, v166
	v_mul_f32_e32 v111, v111, v167
	v_cvt_pk_bf16_f32 v168, -v108, -v109
	v_cvt_pk_bf16_f32 v169, -v110, -v111
	ds_write_b64 v115, v[168:169] offset:23840
	ds_read_b128 v[120:123], v116 offset:26112
	ds_read_b128 v[142:145], v116 offset:30464
	ds_read_b128 v[124:127], v116 offset:26176
	ds_read_b128 v[146:149], v116 offset:30528
	ds_read_b128 v[128:131], v116 offset:26240
	ds_read_b128 v[150:153], v116 offset:30592
	ds_read_b128 v[132:135], v116 offset:26304
	ds_read_b128 v[154:157], v116 offset:30656
	ds_read_b32 v112, v117 offset:192
	ds_read_b32 v113, v117 offset:2240
	ds_read_b128 v[160:163], v114 offset:128
	s_waitcnt lgkmcnt(9)
	v_mfma_f32_16x16x32_bf16 v[108:111], v[120:123], v[142:145], 0
	s_waitcnt lgkmcnt(7)
	v_mfma_f32_16x16x32_bf16 v[108:111], v[124:127], v[146:149], v[108:111]
	s_waitcnt lgkmcnt(5)
	v_mfma_f32_16x16x32_bf16 v[108:111], v[128:131], v[150:153], v[108:111]
	s_waitcnt lgkmcnt(3)
	v_mfma_f32_16x16x32_bf16 v[108:111], v[132:135], v[154:157], v[108:111]
	s_waitcnt lgkmcnt(0)
	v_sub_f32_e32 v164, v112, v160
	v_sub_f32_e32 v165, v112, v161
	v_sub_f32_e32 v166, v112, v162
	v_sub_f32_e32 v167, v112, v163
	v_mul_f32_e32 v164, 0x3fb8aa3b, v164
	v_mul_f32_e32 v165, 0x3fb8aa3b, v165
	v_mul_f32_e32 v166, 0x3fb8aa3b, v166
	v_mul_f32_e32 v167, 0x3fb8aa3b, v167
	v_exp_f32_e32 v164, v164
	v_exp_f32_e32 v165, v165
	v_exp_f32_e32 v166, v166
	v_exp_f32_e32 v167, v167
	v_mul_f32_e32 v108, v108, v113
	v_mul_f32_e32 v109, v109, v113
	v_mul_f32_e32 v110, v110, v113
	v_mul_f32_e32 v111, v111, v113
	v_mul_f32_e32 v108, v108, v164
	v_mul_f32_e32 v109, v109, v165
	v_mul_f32_e32 v110, v110, v166
	v_mul_f32_e32 v111, v111, v167
	v_cvt_pk_bf16_f32 v168, -v108, -v109
	v_cvt_pk_bf16_f32 v169, -v110, -v111
	ds_write_b64 v115, v[168:169] offset:23872
	ds_read_b128 v[120:123], v116 offset:17408
	ds_read_b128 v[142:145], v116 offset:0
	ds_read_b128 v[124:127], v116 offset:17472
	ds_read_b128 v[146:149], v116 offset:64
	ds_read_b128 v[128:131], v116 offset:17536
	ds_read_b128 v[150:153], v116 offset:128
	ds_read_b128 v[132:135], v116 offset:17600
	ds_read_b128 v[154:157], v116 offset:192
	ds_read_b32 v112, v117 offset:0
	ds_read_b128 v[160:163], v114 offset:0
	v_cmp_le_i32_e64 s[10:11], 0, v119
	v_cmp_le_i32_e64 s[12:13], 1, v119
	v_cmp_le_i32_e64 s[48:49], 2, v119
	v_cmp_le_i32_e64 s[50:51], 3, v119
	s_waitcnt lgkmcnt(8)
	v_mfma_f32_16x16x32_bf16 v[108:111], v[120:123], v[142:145], 0
	s_waitcnt lgkmcnt(6)
	v_mfma_f32_16x16x32_bf16 v[108:111], v[124:127], v[146:149], v[108:111]
	s_waitcnt lgkmcnt(4)
	v_mfma_f32_16x16x32_bf16 v[108:111], v[128:131], v[150:153], v[108:111]
	s_waitcnt lgkmcnt(2)
	v_mfma_f32_16x16x32_bf16 v[108:111], v[132:135], v[154:157], v[108:111]
	s_waitcnt lgkmcnt(0)
	v_sub_f32_e32 v164, v112, v160
	v_sub_f32_e32 v165, v112, v161
	v_sub_f32_e32 v166, v112, v162
	v_sub_f32_e32 v167, v112, v163
	v_mul_f32_e32 v164, 0x3fb8aa3b, v164
	v_mul_f32_e32 v165, 0x3fb8aa3b, v165
	v_mul_f32_e32 v166, 0x3fb8aa3b, v166
	v_mul_f32_e32 v167, 0x3fb8aa3b, v167
	v_exp_f32_e32 v164, v164
	v_exp_f32_e32 v165, v165
	v_exp_f32_e32 v166, v166
	v_exp_f32_e32 v167, v167
	v_mul_f32_e32 v108, v108, v164
	v_mul_f32_e32 v109, v109, v165
	v_mul_f32_e32 v110, v110, v166
	v_mul_f32_e32 v111, v111, v167
	v_cndmask_b32_e64 v108, 0, v108, s[10:11]
	v_cndmask_b32_e64 v109, 0, v109, s[12:13]
	v_cndmask_b32_e64 v110, 0, v110, s[48:49]
	v_cndmask_b32_e64 v111, 0, v111, s[50:51]
	v_cvt_pk_bf16_f32 v168, v108, v109
	v_cvt_pk_bf16_f32 v169, v110, v111
	ds_write_b64 v115, v[168:169] offset:0
	s_branch .Lgt_end
.Lgt_lo:
	s_cmp_lt_u32 s79, 2
	s_cbranch_scc1 .Lgt_01
	s_cmp_eq_u32 s79, 2
	s_cbranch_scc1 .Lgt_w2
	ds_read_b128 v[120:123], v116 offset:30464
	ds_read_b128 v[142:145], v116 offset:30464
	ds_read_b128 v[124:127], v116 offset:30528
	ds_read_b128 v[146:149], v116 offset:30528
	ds_read_b128 v[128:131], v116 offset:30592
	ds_read_b128 v[150:153], v116 offset:30592
	ds_read_b128 v[132:135], v116 offset:30656
	ds_read_b128 v[154:157], v116 offset:30656
	ds_read_b32 v112, v117 offset:192
	ds_read_b32 v113, v117 offset:2240
	ds_read_b128 v[160:163], v114 offset:192
	v_cmp_lt_i32_e64 s[10:11], 0, v119
	v_cmp_lt_i32_e64 s[12:13], 1, v119
	v_cmp_lt_i32_e64 s[48:49], 2, v119
	v_cmp_lt_i32_e64 s[50:51], 3, v119
	s_waitcnt lgkmcnt(9)
	v_mfma_f32_16x16x32_bf16 v[108:111], v[120:123], v[142:145], 0
	s_waitcnt lgkmcnt(7)
	v_mfma_f32_16x16x32_bf16 v[108:111], v[124:127], v[146:149], v[108:111]
	s_waitcnt lgkmcnt(5)
	v_mfma_f32_16x16x32_bf16 v[108:111], v[128:131], v[150:153], v[108:111]
	s_waitcnt lgkmcnt(3)
	v_mfma_f32_16x16x32_bf16 v[108:111], v[132:135], v[154:157], v[108:111]
	s_waitcnt lgkmcnt(0)
	v_sub_f32_e32 v164, v112, v160
	v_sub_f32_e32 v165, v112, v161
	v_sub_f32_e32 v166, v112, v162
	v_sub_f32_e32 v167, v112, v163
	v_mul_f32_e32 v164, 0x3fb8aa3b, v164
	v_mul_f32_e32 v165, 0x3fb8aa3b, v165
	v_mul_f32_e32 v166, 0x3fb8aa3b, v166
	v_mul_f32_e32 v167, 0x3fb8aa3b, v167
	v_exp_f32_e32 v164, v164
	v_exp_f32_e32 v165, v165
	v_exp_f32_e32 v166, v166
	v_exp_f32_e32 v167, v167
	v_mul_f32_e32 v108, v108, v113
	v_mul_f32_e32 v109, v109, v113
	v_mul_f32_e32 v110, v110, v113
	v_mul_f32_e32 v111, v111, v113
	v_mul_f32_e32 v108, v108, v164
	v_mul_f32_e32 v109, v109, v165
	v_mul_f32_e32 v110, v110, v166
	v_mul_f32_e32 v111, v111, v167
	v_cndmask_b32_e64 v108, 0, v108, s[10:11]
	v_cndmask_b32_e64 v109, 0, v109, s[12:13]
	v_cndmask_b32_e64 v110, 0, v110, s[48:49]
	v_cndmask_b32_e64 v111, 0, v111, s[50:51]
	v_cvt_pk_bf16_f32 v168, -v108, -v109
	v_cvt_pk_bf16_f32 v169, -v110, -v111
	ds_write_b64 v115, v[168:169] offset:23904
	ds_write_b32 v136, v108 offset:0
	ds_write_b32 v136, v109 offset:80
	ds_write_b32 v136, v110 offset:160
	ds_write_b32 v136, v111 offset:240
	s_branch .Lgt_inv
.Lgt_w2:
	ds_read_b128 v[120:123], v116 offset:26112
	ds_read_b128 v[142:145], v116 offset:26112
	ds_read_b128 v[124:127], v116 offset:26176
	ds_read_b128 v[146:149], v116 offset:26176
	ds_read_b128 v[128:131], v116 offset:26240
	ds_read_b128 v[150:153], v116 offset:26240
	ds_read_b128 v[132:135], v116 offset:26304
	ds_read_b128 v[154:157], v116 offset:26304
	ds_read_b32 v112, v117 offset:128
	ds_read_b32 v113, v117 offset:2176
	ds_read_b128 v[160:163], v114 offset:128
	v_cmp_lt_i32_e64 s[10:11], 0, v119
	v_cmp_lt_i32_e64 s[12:13], 1, v119
	v_cmp_lt_i32_e64 s[48:49], 2, v119
	v_cmp_lt_i32_e64 s[50:51], 3, v119
	s_waitcnt lgkmcnt(9)
	v_mfma_f32_16x16x32_bf16 v[108:111], v[120:123], v[142:145], 0
	s_waitcnt lgkmcnt(7)
	v_mfma_f32_16x16x32_bf16 v[108:111], v[124:127], v[146:149], v[108:111]
	s_waitcnt lgkmcnt(5)
	v_mfma_f32_16x16x32_bf16 v[108:111], v[128:131], v[150:153], v[108:111]
	s_waitcnt lgkmcnt(3)
	v_mfma_f32_16x16x32_bf16 v[108:111], v[132:135], v[154:157], v[108:111]
	s_waitcnt lgkmcnt(0)
	v_sub_f32_e32 v164, v112, v160
	v_sub_f32_e32 v165, v112, v161
	v_sub_f32_e32 v166, v112, v162
	v_sub_f32_e32 v167, v112, v163
	v_mul_f32_e32 v164, 0x3fb8aa3b, v164
	v_mul_f32_e32 v165, 0x3fb8aa3b, v165
	v_mul_f32_e32 v166, 0x3fb8aa3b, v166
	v_mul_f32_e32 v167, 0x3fb8aa3b, v167
	v_exp_f32_e32 v164, v164
	v_exp_f32_e32 v165, v165
	v_exp_f32_e32 v166, v166
	v_exp_f32_e32 v167, v167
	v_mul_f32_e32 v108, v108, v113
	v_mul_f32_e32 v109, v109, v113
	v_mul_f32_e32 v110, v110, v113
	v_mul_f32_e32 v111, v111, v113
	v_mul_f32_e32 v108, v108, v164
	v_mul_f32_e32 v109, v109, v165
	v_mul_f32_e32 v110, v110, v166
	v_mul_f32_e32 v111, v111, v167
	v_cndmask_b32_e64 v108, 0, v108, s[10:11]
	v_cndmask_b32_e64 v109, 0, v109, s[12:13]
	v_cndmask_b32_e64 v110, 0, v110, s[48:49]
	v_cndmask_b32_e64 v111, 0, v111, s[50:51]
	v_cvt_pk_bf16_f32 v168, -v108, -v109
	v_cvt_pk_bf16_f32 v169, -v110, -v111
	ds_write_b64 v115, v[168:169] offset:21568
	ds_write_b32 v136, v108 offset:0
	ds_write_b32 v136, v109 offset:80
	ds_write_b32 v136, v110 offset:160
	ds_write_b32 v136, v111 offset:240
	s_branch .Lgt_inv
.Lgt_01:
	s_cmp_eq_u32 s79, 0
	s_cbranch_scc1 .Lgt_w0
	ds_read_b128 v[120:123], v116 offset:21760
	ds_read_b128 v[142:145], v116 offset:21760
	ds_read_b128 v[124:127], v116 offset:21824
	ds_read_b128 v[146:149], v116 offset:21824
	ds_read_b128 v[128:131], v116 offset:21888
	ds_read_b128 v[150:153], v116 offset:21888
	ds_read_b128 v[132:135], v116 offset:21952
	ds_read_b128 v[154:157], v116 offset:21952
	ds_read_b32 v112, v117 offset:64
	ds_read_b32 v113, v117 offset:2112
	ds_read_b128 v[160:163], v114 offset:64
	v_cmp_lt_i32_e64 s[10:11], 0, v119
	v_cmp_lt_i32_e64 s[12:13], 1, v119
	v_cmp_lt_i32_e64 s[48:49], 2, v119
	v_cmp_lt_i32_e64 s[50:51], 3, v119
	s_waitcnt lgkmcnt(9)
	v_mfma_f32_16x16x32_bf16 v[108:111], v[120:123], v[142:145], 0
	s_waitcnt lgkmcnt(7)
	v_mfma_f32_16x16x32_bf16 v[108:111], v[124:127], v[146:149], v[108:111]
	s_waitcnt lgkmcnt(5)
	v_mfma_f32_16x16x32_bf16 v[108:111], v[128:131], v[150:153], v[108:111]
	s_waitcnt lgkmcnt(3)
	v_mfma_f32_16x16x32_bf16 v[108:111], v[132:135], v[154:157], v[108:111]
	s_waitcnt lgkmcnt(0)
	v_sub_f32_e32 v164, v112, v160
	v_sub_f32_e32 v165, v112, v161
	v_sub_f32_e32 v166, v112, v162
	v_sub_f32_e32 v167, v112, v163
	v_mul_f32_e32 v164, 0x3fb8aa3b, v164
	v_mul_f32_e32 v165, 0x3fb8aa3b, v165
	v_mul_f32_e32 v166, 0x3fb8aa3b, v166
	v_mul_f32_e32 v167, 0x3fb8aa3b, v167
	v_exp_f32_e32 v164, v164
	v_exp_f32_e32 v165, v165
	v_exp_f32_e32 v166, v166
	v_exp_f32_e32 v167, v167
	v_mul_f32_e32 v108, v108, v113
	v_mul_f32_e32 v109, v109, v113
	v_mul_f32_e32 v110, v110, v113
	v_mul_f32_e32 v111, v111, v113
	v_mul_f32_e32 v108, v108, v164
	v_mul_f32_e32 v109, v109, v165
	v_mul_f32_e32 v110, v110, v166
	v_mul_f32_e32 v111, v111, v167
	v_cndmask_b32_e64 v108, 0, v108, s[10:11]
	v_cndmask_b32_e64 v109, 0, v109, s[12:13]
	v_cndmask_b32_e64 v110, 0, v110, s[48:49]
	v_cndmask_b32_e64 v111, 0, v111, s[50:51]
	v_cvt_pk_bf16_f32 v168, -v108, -v109
	v_cvt_pk_bf16_f32 v169, -v110, -v111
	ds_write_b64 v115, v[168:169] offset:19232
	ds_write_b32 v136, v108 offset:0
	ds_write_b32 v136, v109 offset:80
	ds_write_b32 v136, v110 offset:160
	ds_write_b32 v136, v111 offset:240
	s_branch .Lgt_inv
.Lgt_w0:
	ds_read_b128 v[120:123], v116 offset:17408
	ds_read_b128 v[142:145], v116 offset:17408
	ds_read_b128 v[124:127], v116 offset:17472
	ds_read_b128 v[146:149], v116 offset:17472
	ds_read_b128 v[128:131], v116 offset:17536
	ds_read_b128 v[150:153], v116 offset:17536
	ds_read_b128 v[132:135], v116 offset:17600
	ds_read_b128 v[154:157], v116 offset:17600
	ds_read_b32 v112, v117 offset:0
	ds_read_b32 v113, v117 offset:2048
	ds_read_b128 v[160:163], v114 offset:0
	v_cmp_lt_i32_e64 s[10:11], 0, v119
	v_cmp_lt_i32_e64 s[12:13], 1, v119
	v_cmp_lt_i32_e64 s[48:49], 2, v119
	v_cmp_lt_i32_e64 s[50:51], 3, v119
	s_waitcnt lgkmcnt(9)
	v_mfma_f32_16x16x32_bf16 v[108:111], v[120:123], v[142:145], 0
	s_waitcnt lgkmcnt(7)
	v_mfma_f32_16x16x32_bf16 v[108:111], v[124:127], v[146:149], v[108:111]
	s_waitcnt lgkmcnt(5)
	v_mfma_f32_16x16x32_bf16 v[108:111], v[128:131], v[150:153], v[108:111]
	s_waitcnt lgkmcnt(3)
	v_mfma_f32_16x16x32_bf16 v[108:111], v[132:135], v[154:157], v[108:111]
	s_waitcnt lgkmcnt(0)
	v_sub_f32_e32 v164, v112, v160
	v_sub_f32_e32 v165, v112, v161
	v_sub_f32_e32 v166, v112, v162
	v_sub_f32_e32 v167, v112, v163
	v_mul_f32_e32 v164, 0x3fb8aa3b, v164
	v_mul_f32_e32 v165, 0x3fb8aa3b, v165
	v_mul_f32_e32 v166, 0x3fb8aa3b, v166
	v_mul_f32_e32 v167, 0x3fb8aa3b, v167
	v_exp_f32_e32 v164, v164
	v_exp_f32_e32 v165, v165
	v_exp_f32_e32 v166, v166
	v_exp_f32_e32 v167, v167
	v_mul_f32_e32 v108, v108, v113
	v_mul_f32_e32 v109, v109, v113
	v_mul_f32_e32 v110, v110, v113
	v_mul_f32_e32 v111, v111, v113
	v_mul_f32_e32 v108, v108, v164
	v_mul_f32_e32 v109, v109, v165
	v_mul_f32_e32 v110, v110, v166
	v_mul_f32_e32 v111, v111, v167
	v_cndmask_b32_e64 v108, 0, v108, s[10:11]
	v_cndmask_b32_e64 v109, 0, v109, s[12:13]
	v_cndmask_b32_e64 v110, 0, v110, s[48:49]
	v_cndmask_b32_e64 v111, 0, v111, s[50:51]
	v_cvt_pk_bf16_f32 v168, -v108, -v109
	v_cvt_pk_bf16_f32 v169, -v110, -v111
	ds_write_b64 v115, v[168:169] offset:16896
	ds_write_b32 v136, v108 offset:0
	ds_write_b32 v136, v109 offset:80
	ds_write_b32 v136, v110 offset:160
	ds_write_b32 v136, v111 offset:240
.Lgt_inv:
	v_cmp_gt_u32_e32 vcc, 16, v3
	s_and_saveexec_b64 s[10:11], vcc
	s_cbranch_execz .Lgt_invend
	v_mov_b32_e32 v119, s97
	ds_read_b128 v[120:123], v119 offset:0
	ds_read_b128 v[124:127], v119 offset:16
	ds_read_b128 v[128:131], v119 offset:32
	ds_read_b128 v[132:135], v119 offset:48
	ds_read_b128 v[142:145], v119 offset:80
	ds_read_b128 v[146:149], v119 offset:96
	ds_read_b128 v[150:153], v119 offset:112
	ds_read_b128 v[154:157], v119 offset:128
	ds_read_b128 v[158:161], v119 offset:160
	ds_read_b128 v[236:239], v119 offset:176
	ds_read_b128 v[240:243], v119 offset:192
	ds_read_b128 v[244:247], v119 offset:208
	ds_read_b128 v[248:251], v119 offset:256
	ds_read_b128 v[252:255], v119 offset:272
	ds_read_b128 v[108:111], v119 offset:288
	ds_read_b128 v[112:115], v119 offset:336
	s_mov_b64 s[12:13], 0x1
	v_cndmask_b32_e64 v210, 0, 1.0, s[12:13]
	s_mov_b64 s[48:49], 0x2
	v_cndmask_b32_e64 v211, 0, 1.0, s[48:49]
	s_mov_b64 s[50:51], 0x4
	v_cndmask_b32_e64 v212, 0, 1.0, s[50:51]
	s_mov_b64 s[12:13], 0x8
	v_cndmask_b32_e64 v213, 0, 1.0, s[12:13]
	s_mov_b64 s[48:49], 0x10
	v_cndmask_b32_e64 v214, 0, 1.0, s[48:49]
	s_mov_b64 s[50:51], 0x20
	v_cndmask_b32_e64 v215, 0, 1.0, s[50:51]
	s_mov_b64 s[12:13], 0x40
	v_cndmask_b32_e64 v216, 0, 1.0, s[12:13]
	s_mov_b64 s[48:49], 0x80
	v_cndmask_b32_e64 v217, 0, 1.0, s[48:49]
	s_mov_b64 s[50:51], 0x100
	v_cndmask_b32_e64 v218, 0, 1.0, s[50:51]
	s_mov_b64 s[12:13], 0x200
	v_cndmask_b32_e64 v219, 0, 1.0, s[12:13]
	s_mov_b64 s[48:49], 0x400
	v_cndmask_b32_e64 v187, 0, 1.0, s[48:49]
	s_mov_b64 s[50:51], 0x800
	v_cndmask_b32_e64 v164, 0, 1.0, s[50:51]
	s_mov_b64 s[12:13], 0x1000
	v_cndmask_b32_e64 v165, 0, 1.0, s[12:13]
	s_mov_b64 s[48:49], 0x2000
	v_cndmask_b32_e64 v166, 0, 1.0, s[48:49]
	s_mov_b64 s[50:51], 0x4000
	v_cndmask_b32_e64 v167, 0, 1.0, s[50:51]
	s_mov_b64 s[12:13], 0x8000
	v_cndmask_b32_e64 v168, 0, 1.0, s[12:13]
	s_waitcnt lgkmcnt(12)
	v_fma_f32 v211, -v121, v210, v211
	v_fma_f32 v212, -v122, v210, v212
	v_fma_f32 v213, -v123, v210, v213
	v_fma_f32 v214, -v124, v210, v214
	v_fma_f32 v215, -v125, v210, v215
	v_fma_f32 v216, -v126, v210, v216
	v_fma_f32 v217, -v127, v210, v217
	v_fma_f32 v218, -v128, v210, v218
	v_fma_f32 v219, -v129, v210, v219
	v_fma_f32 v187, -v130, v210, v187
	v_fma_f32 v164, -v131, v210, v164
	v_fma_f32 v165, -v132, v210, v165
	v_fma_f32 v166, -v133, v210, v166
	v_fma_f32 v167, -v134, v210, v167
	v_fma_f32 v168, -v135, v210, v168
	ds_read_b128 v[120:123], v119 offset:352
	ds_read_b128 v[124:127], v119 offset:368
	ds_read_b128 v[128:131], v119 offset:416
	ds_read_b128 v[132:135], v119 offset:432
	s_waitcnt lgkmcnt(12)
	v_fma_f32 v212, -v144, v211, v212
	v_fma_f32 v213, -v145, v211, v213
	v_fma_f32 v214, -v146, v211, v214
	v_fma_f32 v215, -v147, v211, v215
	v_fma_f32 v216, -v148, v211, v216
	v_fma_f32 v217, -v149, v211, v217
	v_fma_f32 v218, -v150, v211, v218
	v_fma_f32 v219, -v151, v211, v219
	v_fma_f32 v187, -v152, v211, v187
	v_fma_f32 v164, -v153, v211, v164
	v_fma_f32 v165, -v154, v211, v165
	v_fma_f32 v166, -v155, v211, v166
	v_fma_f32 v167, -v156, v211, v167
	v_fma_f32 v168, -v157, v211, v168
	ds_read_b128 v[142:145], v119 offset:448
	ds_read_b128 v[146:149], v119 offset:496
	ds_read_b128 v[150:153], v119 offset:512
	ds_read_b128 v[154:157], v119 offset:528
	s_waitcnt lgkmcnt(12)
	v_fma_f32 v213, -v161, v212, v213
	v_fma_f32 v214, -v236, v212, v214
	v_fma_f32 v215, -v237, v212, v215
	v_fma_f32 v216, -v238, v212, v216
	v_fma_f32 v217, -v239, v212, v217
	v_fma_f32 v218, -v240, v212, v218
	v_fma_f32 v219, -v241, v212, v219
	v_fma_f32 v187, -v242, v212, v187
	v_fma_f32 v164, -v243, v212, v164
	v_fma_f32 v165, -v244, v212, v165
	v_fma_f32 v166, -v245, v212, v166
	v_fma_f32 v167, -v246, v212, v167
	v_fma_f32 v168, -v247, v212, v168
	ds_read_b128 v[158:161], v119 offset:592
	ds_read_b128 v[236:239], v119 offset:608
	ds_read_b128 v[240:243], v119 offset:672
	ds_read_b128 v[244:247], v119 offset:688
	s_waitcnt lgkmcnt(13)
	v_fma_f32 v214, -v248, v213, v214
	v_fma_f32 v215, -v249, v213, v215
	v_fma_f32 v216, -v250, v213, v216
	v_fma_f32 v217, -v251, v213, v217
	v_fma_f32 v218, -v252, v213, v218
	v_fma_f32 v219, -v253, v213, v219
	v_fma_f32 v187, -v254, v213, v187
	v_fma_f32 v164, -v255, v213, v164
	v_fma_f32 v165, -v108, v213, v165
	v_fma_f32 v166, -v109, v213, v166
	v_fma_f32 v167, -v110, v213, v167
	v_fma_f32 v168, -v111, v213, v168
	ds_read_b128 v[248:251], v119 offset:752
	ds_read_b128 v[252:255], v119 offset:768
	ds_read_b128 v[108:111], v119 offset:832
	s_waitcnt lgkmcnt(13)
	v_fma_f32 v215, -v113, v214, v215
	v_fma_f32 v216, -v114, v214, v216
	v_fma_f32 v217, -v115, v214, v217
	v_fma_f32 v218, -v120, v214, v218
	v_fma_f32 v219, -v121, v214, v219
	v_fma_f32 v187, -v122, v214, v187
	v_fma_f32 v164, -v123, v214, v164
	v_fma_f32 v165, -v124, v214, v165
	v_fma_f32 v166, -v125, v214, v166
	v_fma_f32 v167, -v126, v214, v167
	v_fma_f32 v168, -v127, v214, v168
	ds_read_b128 v[112:115], v119 offset:848
	ds_read_b128 v[120:123], v119 offset:928
	ds_read_b128 v[124:127], v119 offset:1008
	s_waitcnt lgkmcnt(13)
	v_fma_f32 v216, -v130, v215, v216
	v_fma_f32 v217, -v131, v215, v217
	v_fma_f32 v218, -v132, v215, v218
	v_fma_f32 v219, -v133, v215, v219
	v_fma_f32 v187, -v134, v215, v187
	v_fma_f32 v164, -v135, v215, v164
	v_fma_f32 v165, -v142, v215, v165
	v_fma_f32 v166, -v143, v215, v166
	v_fma_f32 v167, -v144, v215, v167
	v_fma_f32 v168, -v145, v215, v168
	ds_read_b128 v[128:131], v119 offset:1088
	ds_read_b128 v[132:135], v119 offset:1168
	s_waitcnt lgkmcnt(12)
	v_fma_f32 v217, -v149, v216, v217
	v_fma_f32 v218, -v150, v216, v218
	v_fma_f32 v219, -v151, v216, v219
	v_fma_f32 v187, -v152, v216, v187
	v_fma_f32 v164, -v153, v216, v164
	v_fma_f32 v165, -v154, v216, v165
	v_fma_f32 v166, -v155, v216, v166
	v_fma_f32 v167, -v156, v216, v167
	v_fma_f32 v168, -v157, v216, v168
	s_waitcnt lgkmcnt(10)
	v_fma_f32 v218, -v158, v217, v218
	v_fma_f32 v219, -v159, v217, v219
	v_fma_f32 v187, -v160, v217, v187
	v_fma_f32 v164, -v161, v217, v164
	v_fma_f32 v165, -v236, v217, v165
	v_fma_f32 v166, -v237, v217, v166
	v_fma_f32 v167, -v238, v217, v167
	v_fma_f32 v168, -v239, v217, v168
	s_waitcnt lgkmcnt(8)
	v_fma_f32 v219, -v241, v218, v219
	v_fma_f32 v187, -v242, v218, v187
	v_fma_f32 v164, -v243, v218, v164
	v_fma_f32 v165, -v244, v218, v165
	v_fma_f32 v166, -v245, v218, v166
	v_fma_f32 v167, -v246, v218, v167
	v_fma_f32 v168, -v247, v218, v168
	s_waitcnt lgkmcnt(6)
	v_fma_f32 v187, -v250, v219, v187
	v_fma_f32 v164, -v251, v219, v164
	v_fma_f32 v165, -v252, v219, v165
	v_fma_f32 v166, -v253, v219, v166
	v_fma_f32 v167, -v254, v219, v167
	v_fma_f32 v168, -v255, v219, v168
	s_waitcnt lgkmcnt(4)
	v_fma_f32 v164, -v111, v187, v164
	v_fma_f32 v165, -v112, v187, v165
	v_fma_f32 v166, -v113, v187, v166
	v_fma_f32 v167, -v114, v187, v167
	v_fma_f32 v168, -v115, v187, v168
	s_waitcnt lgkmcnt(3)
	v_fma_f32 v165, -v120, v164, v165
	v_fma_f32 v166, -v121, v164, v166
	v_fma_f32 v167, -v122, v164, v167
	v_fma_f32 v168, -v123, v164, v168
	s_waitcnt lgkmcnt(2)
	v_fma_f32 v166, -v125, v165, v166
	v_fma_f32 v167, -v126, v165, v167
	v_fma_f32 v168, -v127, v165, v168
	s_waitcnt lgkmcnt(1)
	v_fma_f32 v167, -v130, v166, v167
	v_fma_f32 v168, -v131, v166, v168
	s_waitcnt lgkmcnt(0)
	v_fma_f32 v168, -v135, v167, v168
	v_lshl_add_u32 v169, v3, 1, s88
	v_cvt_pk_bf16_f32 v170, v210, s0
	ds_write_b16 v169, v170 offset:0
	v_cvt_pk_bf16_f32 v171, v211, s0
	ds_write_b16 v169, v171 offset:40
	v_cvt_pk_bf16_f32 v170, v212, s0
	ds_write_b16 v169, v170 offset:80
	v_cvt_pk_bf16_f32 v171, v213, s0
	ds_write_b16 v169, v171 offset:120
	v_cvt_pk_bf16_f32 v170, v214, s0
	ds_write_b16 v169, v170 offset:160
	v_cvt_pk_bf16_f32 v171, v215, s0
	ds_write_b16 v169, v171 offset:200
	v_cvt_pk_bf16_f32 v170, v216, s0
	ds_write_b16 v169, v170 offset:240
	v_cvt_pk_bf16_f32 v171, v217, s0
	ds_write_b16 v169, v171 offset:280
	v_cvt_pk_bf16_f32 v170, v218, s0
	ds_write_b16 v169, v170 offset:320
	v_cvt_pk_bf16_f32 v171, v219, s0
	ds_write_b16 v169, v171 offset:360
	v_cvt_pk_bf16_f32 v170, v187, s0
	ds_write_b16 v169, v170 offset:400
	v_cvt_pk_bf16_f32 v171, v164, s0
	ds_write_b16 v169, v171 offset:440
	v_cvt_pk_bf16_f32 v170, v165, s0
	ds_write_b16 v169, v170 offset:480
	v_cvt_pk_bf16_f32 v171, v166, s0
	ds_write_b16 v169, v171 offset:520
	v_cvt_pk_bf16_f32 v170, v167, s0
	ds_write_b16 v169, v170 offset:560
	v_cvt_pk_bf16_f32 v171, v168, s0
	ds_write_b16 v169, v171 offset:600
